# compressed-attention second pass: hand-written loop for the far key blocks (K two steps, V one step ahead); compiled G != 256 retention fallback removed to keep branch offsets in range
# baseline (speedup 1.0000x reference)
.LBB0_597:
	ds_bpermute_b32 v1, v81, v32
	v_max_f32_e32 v2, v32, v32
	ds_bpermute_b32 v5, v81, v0
	s_and_b64 vcc, exec, s[0:1]
	s_waitcnt lgkmcnt(0)
	v_max_f32_e32 v3, v1, v1
	v_max_f32_e32 v2, v2, v3
	v_sub_f32_e32 v1, v1, v2
	v_sub_f32_e32 v3, v32, v2
	v_mul_f32_e32 v1, 0x3fb8aa3b, v1
	v_mul_f32_e32 v3, 0x3fb8aa3b, v3
	v_exp_f32_e32 v1, v1
	v_exp_f32_e32 v4, v3
	v_mul_f32_e32 v6, v1, v5
	v_pk_fma_f32 v[0:1], v[0:1], v[4:5], v[6:7] op_sel_hi:[1,1,0]
	ds_bpermute_b32 v1, v100, v2
	ds_bpermute_b32 v3, v100, v0
	s_cbranch_vccz .LBB0_623
	s_waitcnt lgkmcnt(0)
	v_max_f32_e32 v4, v1, v1
	v_max_f32_e32 v5, v2, v2
	v_max_f32_e32 v85, v5, v4
	v_sub_f32_e32 v2, v2, v85
	v_sub_f32_e32 v1, v1, v85
	v_mul_f32_e32 v2, 0x3fb8aa3b, v2
	v_mul_f32_e32 v1, 0x3fb8aa3b, v1
	v_exp_f32_e32 v2, v2
	v_exp_f32_e32 v1, v1
	v_mov_b32_e32 v143, 0
	s_add_i32 s4, s57, 0xfffffdf1
	s_mov_b32 s5, 0
	v_pk_mul_f32 v[0:1], v[0:1], v[2:3]
	v_mov_b32_e32 v87, v78
	v_add_f32_e32 v0, v0, v1
	v_div_scale_f32 v1, s[0:1], v0, v0, 1.0
	v_rcp_f32_e32 v2, v1
	v_mov_b32_e32 v44, 0
	v_mov_b32_e32 v45, v143
	v_mov_b32_e32 v46, v143
	v_fma_f32 v3, -v1, v2, 1.0
	v_fmac_f32_e32 v2, v3, v2
	v_div_scale_f32 v3, vcc, 1.0, v0, 1.0
	v_mul_f32_e32 v4, v3, v2
	v_fma_f32 v5, -v1, v4, v3
	v_fmac_f32_e32 v4, v5, v2
	v_fma_f32 v1, -v1, v4, v3
	v_div_fmas_f32 v1, v1, v2, v4
	v_div_fixup_f32 v1, v1, v0, 1.0
	v_cmp_lt_f32_e32 vcc, 0, v0
	v_lshlrev_b32_e32 v0, 17, v141
	v_mov_b32_e32 v47, v143
	v_cndmask_b32_e32 v90, 0, v1, vcc
	v_mov_b32_e32 v1, v65
	v_lshl_add_u64 v[92:93], v[82:83], 0, v[0:1]
	v_mov_b32_e32 v91, v90
	v_mov_b32_e32 v94, v90
	v_mov_b32_e32 v95, v90
	v_mov_b32_e32 v96, v90
	v_mov_b32_e32 v97, v90
	v_mov_b32_e32 v98, v90
	v_mov_b32_e32 v99, v90
	v_mov_b32_e32 v40, 0
	v_mov_b32_e32 v41, v143
	v_mov_b32_e32 v42, v143
	v_mov_b32_e32 v43, v143
	v_mov_b32_e32 v36, 0
	v_mov_b32_e32 v37, v143
	v_mov_b32_e32 v38, v143
	v_mov_b32_e32 v39, v143
	v_mov_b32_e32 v32, 0
	v_mov_b32_e32 v33, v143
	v_mov_b32_e32 v34, v143
	v_mov_b32_e32 v35, v143
	s_add_i32 s88, s4, 0xfffff9c0
	s_ashr_i32 s88, s88, 9
	s_add_i32 s88, s88, 1
	s_max_i32 s88, s88, 0
	s_add_i32 s89, s61, -1
	s_min_i32 s88, s88, s89
	s_min_i32 s88, s88, 31
	s_cmp_lt_i32 s88, 1
	s_cbranch_scc1 .Lcp2_done
	s_mov_b32 s86, 0x3e38aa3b
	s_mov_b32 s87, 0x3e38aa3b
	s_add_i32 s90, s62, 0x7c0
	v_mov_b32_e32 v170, s90
	ds_read_b32 v168, v170
	global_load_dwordx4 v[60:63], v[92:93], off offset:0
	global_load_dwordx4 v[56:59], v[92:93], off offset:1024
	global_load_dwordx4 v[52:55], v[92:93], off offset:2048
	global_load_dwordx4 v[48:51], v[92:93], off offset:3072
	s_min_i32 s90, 1, s89
	s_lshl_b32 s90, s90, 12
	s_mov_b32 s91, 0
	v_lshl_add_u64 v[166:167], v[88:89], 0, s[90:91]
	global_load_dwordx4 v[150:153], v[166:167], off offset:0
	global_load_dwordx4 v[154:157], v[166:167], off offset:1024
	global_load_dwordx4 v[158:161], v[166:167], off offset:2048
	global_load_dwordx4 v[162:165], v[166:167], off offset:3072
	s_waitcnt lgkmcnt(0)
	v_sub_f32_e32 v168, v168, v85
	v_mul_f32_e32 v168, 0x3fb8aa3b, v168
.Lcp2_A:
	s_waitcnt vmcnt(4) lgkmcnt(0)
	s_cmp_lt_i32 s88, 2
	s_cbranch_scc1 .Lcp2_A_nov
	v_lshl_add_u64 v[166:167], v[92:93], 0, s[74:75]
	global_load_dwordx4 v[174:177], v[166:167], off offset:0
	global_load_dwordx4 v[178:181], v[166:167], off offset:1024
	global_load_dwordx4 v[182:185], v[166:167], off offset:2048
	global_load_dwordx4 v[186:189], v[166:167], off offset:3072
.Lcp2_A_nov:
	v_mfma_f32_16x16x32_bf16 v[70:73], v[16:19], v[8:11], 0
	v_mfma_f32_16x16x32_bf16 v[4:7], v[24:27], v[8:11], 0
	v_mfma_f32_16x16x32_bf16 v[70:73], v[20:23], v[12:15], v[70:73]
	v_mfma_f32_16x16x32_bf16 v[66:69], v[28:31], v[12:15], v[4:7]
	s_cmp_lt_i32 s88, 2
	s_cbranch_scc1 .Lcp2_A_nok
	s_add_i32 s90, s5, 2
	s_min_i32 s90, s90, s89
	s_lshl_b32 s90, s90, 12
	v_lshl_add_u64 v[166:167], v[88:89], 0, s[90:91]
	global_load_dwordx4 v[16:19], v[166:167], off offset:0
	global_load_dwordx4 v[20:23], v[166:167], off offset:1024
	global_load_dwordx4 v[24:27], v[166:167], off offset:2048
	global_load_dwordx4 v[28:31], v[166:167], off offset:3072
	s_branch .Lcp2_A_go

.Lcp2_A_go:
	s_nop 7
	v_pk_fma_f32 v[0:1], v[70:71], s[86:87], v[168:169] op_sel_hi:[1,0,0]
	v_pk_fma_f32 v[2:3], v[72:73], s[86:87], v[168:169] op_sel_hi:[1,0,0]
	v_pk_fma_f32 v[4:5], v[66:67], s[86:87], v[168:169] op_sel_hi:[1,0,0]
	v_pk_fma_f32 v[6:7], v[68:69], s[86:87], v[168:169] op_sel_hi:[1,0,0]
	v_exp_f32_e32 v0, v0
	v_exp_f32_e32 v1, v1
	v_exp_f32_e32 v2, v2
	v_exp_f32_e32 v3, v3
	v_exp_f32_e32 v4, v4
	v_exp_f32_e32 v5, v5
	v_exp_f32_e32 v6, v6
	v_exp_f32_e32 v7, v7
	s_nop 0
	v_pk_mul_f32 v[6:7], v[98:99], v[6:7]
	v_pk_mul_f32 v[4:5], v[96:97], v[4:5]
	v_pk_mul_f32 v[2:3], v[94:95], v[2:3]
	v_pk_mul_f32 v[0:1], v[90:91], v[0:1]
	s_nop 0
	v_cvt_pk_bf16_f32 v66, v0, v1
	v_cvt_pk_bf16_f32 v67, v2, v3
	v_cvt_pk_bf16_f32 v68, v4, v5
	v_cvt_pk_bf16_f32 v69, v6, v7
	v_add_f32_e32 v0, v0, v1
	v_add_f32_e32 v1, v2, v3
	v_mfma_f32_16x16x32_bf16 v[44:47], v[60:63], v[66:69], v[44:47]
	ds_bpermute_b32 v190, v101, v3
	v_add_f32_e32 v0, v0, v1
	v_add_f32_e32 v2, v6, v7
	v_mfma_f32_16x16x32_bf16 v[40:43], v[56:59], v[66:69], v[40:43]
	ds_bpermute_b32 v191, v101, v7
	s_waitcnt lgkmcnt(1)
	v_cndmask_b32_e64 v1, v190, v143, s[8:9]
	v_add_f32_e32 v0, v0, v1
	v_mfma_f32_16x16x32_bf16 v[36:39], v[52:55], v[66:69], v[36:39]
	v_add_f32_e32 v1, v4, v5
	v_add_f32_e32 v1, v1, v2
	s_waitcnt lgkmcnt(0)
	v_cndmask_b32_e64 v2, v191, v190, s[8:9]
	v_mfma_f32_16x16x32_bf16 v[32:35], v[48:51], v[66:69], v[32:35]
	s_addk_i32 s4, 0xfe00
	v_add_u32_e32 v192, v140, v87
	v_add_f32_e32 v1, v1, v2
	v_add_u32_e32 v87, 32, v87
	v_lshl_add_u64 v[92:93], v[92:93], 0, s[74:75]
	ds_write2_b32 v192, v0, v1 offset1:4
	v_mov_b32_e32 v143, v191
	s_add_i32 s5, s5, 1
	s_add_i32 s88, s88, -1
	s_cmp_lt_i32 s88, 1
	s_cbranch_scc1 .Lcp2_endA
.Lcp2_B:
	s_waitcnt vmcnt(4) lgkmcnt(0)
	s_cmp_lt_i32 s88, 2
	s_cbranch_scc1 .Lcp2_B_nov
	v_lshl_add_u64 v[166:167], v[92:93], 0, s[74:75]
	global_load_dwordx4 v[60:63], v[166:167], off offset:0
	global_load_dwordx4 v[56:59], v[166:167], off offset:1024
	global_load_dwordx4 v[52:55], v[166:167], off offset:2048
	global_load_dwordx4 v[48:51], v[166:167], off offset:3072
.Lcp2_B_nov:
	v_mfma_f32_16x16x32_bf16 v[70:73], v[150:153], v[8:11], 0
	v_mfma_f32_16x16x32_bf16 v[4:7], v[158:161], v[8:11], 0
	v_mfma_f32_16x16x32_bf16 v[70:73], v[154:157], v[12:15], v[70:73]
	v_mfma_f32_16x16x32_bf16 v[66:69], v[162:165], v[12:15], v[4:7]
	s_cmp_lt_i32 s88, 2
	s_cbranch_scc1 .Lcp2_B_nok
	s_add_i32 s90, s5, 2
	s_min_i32 s90, s90, s89
	s_lshl_b32 s90, s90, 12
	v_lshl_add_u64 v[166:167], v[88:89], 0, s[90:91]
	global_load_dwordx4 v[150:153], v[166:167], off offset:0
	global_load_dwordx4 v[154:157], v[166:167], off offset:1024
	global_load_dwordx4 v[158:161], v[166:167], off offset:2048
	global_load_dwordx4 v[162:165], v[166:167], off offset:3072
	s_branch .Lcp2_B_go

.Lcp2_B_go:
	s_nop 7
	v_pk_fma_f32 v[0:1], v[70:71], s[86:87], v[168:169] op_sel_hi:[1,0,0]
	v_pk_fma_f32 v[2:3], v[72:73], s[86:87], v[168:169] op_sel_hi:[1,0,0]
	v_pk_fma_f32 v[4:5], v[66:67], s[86:87], v[168:169] op_sel_hi:[1,0,0]
	v_pk_fma_f32 v[6:7], v[68:69], s[86:87], v[168:169] op_sel_hi:[1,0,0]
	v_exp_f32_e32 v0, v0
	v_exp_f32_e32 v1, v1
	v_exp_f32_e32 v2, v2
	v_exp_f32_e32 v3, v3
	v_exp_f32_e32 v4, v4
	v_exp_f32_e32 v5, v5
	v_exp_f32_e32 v6, v6
	v_exp_f32_e32 v7, v7
	s_nop 0
	v_pk_mul_f32 v[6:7], v[98:99], v[6:7]
	v_pk_mul_f32 v[4:5], v[96:97], v[4:5]
	v_pk_mul_f32 v[2:3], v[94:95], v[2:3]
	v_pk_mul_f32 v[0:1], v[90:91], v[0:1]
	s_nop 0
	v_cvt_pk_bf16_f32 v66, v0, v1
	v_cvt_pk_bf16_f32 v67, v2, v3
	v_cvt_pk_bf16_f32 v68, v4, v5
	v_cvt_pk_bf16_f32 v69, v6, v7
	v_add_f32_e32 v0, v0, v1
	v_add_f32_e32 v1, v2, v3
	v_mfma_f32_16x16x32_bf16 v[44:47], v[174:177], v[66:69], v[44:47]
	ds_bpermute_b32 v190, v101, v3
	v_add_f32_e32 v0, v0, v1
	v_add_f32_e32 v2, v6, v7
	v_mfma_f32_16x16x32_bf16 v[40:43], v[178:181], v[66:69], v[40:43]
	ds_bpermute_b32 v191, v101, v7
	s_waitcnt lgkmcnt(1)
	v_cndmask_b32_e64 v1, v190, v143, s[8:9]
	v_add_f32_e32 v0, v0, v1
	v_mfma_f32_16x16x32_bf16 v[36:39], v[182:185], v[66:69], v[36:39]
	v_add_f32_e32 v1, v4, v5
	v_add_f32_e32 v1, v1, v2
	s_waitcnt lgkmcnt(0)
	v_cndmask_b32_e64 v2, v191, v190, s[8:9]
	v_mfma_f32_16x16x32_bf16 v[32:35], v[186:189], v[66:69], v[32:35]
	s_addk_i32 s4, 0xfe00
	v_add_u32_e32 v192, v140, v87
	v_add_f32_e32 v1, v1, v2
	v_add_u32_e32 v87, 32, v87
	v_lshl_add_u64 v[92:93], v[92:93], 0, s[74:75]
	ds_write2_b32 v192, v0, v1 offset1:4
	v_mov_b32_e32 v143, v191
	s_add_i32 s5, s5, 1
	s_add_i32 s88, s88, -1
	s_cmp_lt_i32 s88, 1
	s_cbranch_scc0 .Lcp2_A
	s_branch .Lcp2_done

.Lcp2_done:
.LBB0_599:
	s_mov_b32 s2, s5
	s_add_i32 s5, s5, 1
	s_cmp_lt_i32 s5, s61
	s_cselect_b32 s52, s5, s2
	s_waitcnt vmcnt(0)
	v_mov_b64_e32 v[0:1], v[28:29]
	s_lshl_b64 s[0:1], s[52:53], 12
	v_mov_b64_e32 v[2:3], v[30:31]
	v_mov_b64_e32 v[4:5], v[24:25]
	v_mov_b64_e32 v[68:69], v[22:23]
	v_mov_b64_e32 v[72:73], v[18:19]
	v_lshl_add_u64 v[28:29], v[88:89], 0, s[0:1]
	v_mov_b64_e32 v[6:7], v[26:27]
	v_mov_b64_e32 v[66:67], v[20:21]
	v_mov_b64_e32 v[70:71], v[16:17]
	flat_load_dwordx4 v[16:19], v[28:29]
	flat_load_dwordx4 v[20:23], v[28:29] offset:1024
	flat_load_dwordx4 v[24:27], v[28:29] offset:2048
	s_nop 0
	flat_load_dwordx4 v[28:31], v[28:29] offset:3072
	s_nop 0
	flat_load_dwordx4 v[60:63], v[92:93]
	flat_load_dwordx4 v[56:59], v[92:93] offset:1024
	flat_load_dwordx4 v[52:55], v[92:93] offset:2048
	flat_load_dwordx4 v[48:51], v[92:93] offset:3072
	v_mfma_f32_16x16x32_bf16 v[70:73], v[70:73], v[8:11], 0
	s_max_i32 s0, s4, 0
	s_cmp_lt_i32 s4, 16
	s_cselect_b64 vcc, -1, 0
	v_mfma_f32_16x16x32_bf16 v[4:7], v[4:7], v[8:11], 0
	s_cmp_lt_i32 s4, 0
	v_mfma_f32_16x16x32_bf16 v[70:73], v[66:69], v[12:15], v[70:73]
	v_mfma_f32_16x16x32_bf16 v[66:69], v[0:3], v[12:15], v[4:7]
	v_cvt_f32_u32_e32 v0, s0
	v_mov_b32_e32 v1, s0
	s_cselect_b64 s[0:1], -1, 0
	s_cmp_gt_u32 s2, 30
	v_mul_f32_e32 v0, 0x3d800000, v0
	v_log_f32_e32 v0, v0
	s_cselect_b64 s[2:3], -1, 0
	s_or_b64 s[2:3], s[0:1], s[2:3]
	s_mov_b64 s[0:1], 0
	v_mul_f32_e32 v0, 0x40124925, v0
	v_cvt_i32_f32_e32 v0, v0
	v_min_i32_e32 v0, 15, v0
	v_add_u32_e32 v0, 16, v0
	v_cndmask_b32_e32 v0, v0, v1, vcc
	s_and_b64 vcc, exec, s[2:3]
	v_readfirstlane_b32 s6, v0
	s_cbranch_vccnz .LBB0_605
	s_add_i32 s0, s4, 0x1ff
	v_cvt_f32_u32_e32 v0, s0
	v_mul_f32_e32 v0, 0x3d800000, v0
	v_log_f32_e32 v0, v0
	s_nop 0
	v_mul_f32_e32 v0, 0x40124925, v0
	v_cvt_i32_f32_e32 v0, v0
	v_min_i32_e32 v0, 15, v0
	s_nop 0
	v_readfirstlane_b32 s0, v0
	s_add_i32 s2, s0, 16
	s_cmp_lg_u32 s6, s2
	s_mov_b64 s[0:1], -1
	s_cselect_b64 s[2:3], -1, 0
	s_andn2_b64 vcc, exec, s[2:3]
	s_cbranch_vccz .LBB0_606

.Lintra_orig:
.LBB0_748:
	s_add_u32 s12, s26, 0x1e800000
	s_addc_u32 s13, s27, 0
	s_add_u32 s18, s26, 0x1d500000
	s_addc_u32 s19, s27, 0
	s_add_u32 s16, s26, 0x1d900000
	s_addc_u32 s17, s27, 0
	v_mov_b32_e32 v0, v208
	s_add_u32 s14, s26, 0x1ad00000
	s_addc_u32 s15, s27, 0
	v_and_b32_e32 v1, 63, v0
	v_bfe_u32 v2, v0, 4, 2
	v_readlane_b32 s2, v254, 9
	v_and_b32_e32 v3, 15, v0
	v_and_b32_e32 v200, 7, v0
	v_lshlrev_b32_e32 v0, 2, v1
	v_lshlrev_b32_e32 v182, 2, v2
	s_add_u32 s20, s26, 0x1e500002
	v_readlane_b32 s3, v254, 10
	v_lshlrev_b32_e32 v198, 3, v2
	v_lshlrev_b32_e32 v199, 5, v3
	v_xor_b32_e32 v180, 64, v0
	v_xor_b32_e32 v181, 0x80, v0
	v_or_b32_e32 v183, 1, v182
	v_or_b32_e32 v184, 2, v182
	v_or_b32_e32 v185, 3, v182
	v_or_b32_e32 v186, 16, v182
	v_or_b32_e32 v187, 17, v182
	v_or_b32_e32 v188, 18, v182
	v_or_b32_e32 v189, 19, v182
	v_or_b32_e32 v190, 32, v182
	v_or_b32_e32 v191, 33, v182
	v_or_b32_e32 v192, 34, v182
	v_or_b32_e32 v193, 35, v182
	v_or_b32_e32 v194, 48, v182
	v_or_b32_e32 v195, 49, v182
	v_or_b32_e32 v196, 50, v182
	v_or_b32_e32 v197, 51, v182
	v_cmp_gt_u32_e64 s[8:9], 8, v3
	s_addc_u32 s21, s27, 0
	s_mov_b64 s[0:1], -1
	s_and_b64 vcc, exec, s[2:3]
	s_cbranch_vccz .LBB0_841
	s_mov_b64 s[22:23], exec
